# scan: waves 0-3 FLUSH completes after PREP, ahead of the closing LDS wait (explicit wait on the PREP-skipped last chunk)
# speedup vs baseline: 1.0081x; 1.0081x over previous
.Lpq0_end:
	s_and_b64 s[98:99], s[54:55], exec
	s_cbranch_scc0 .Lfl0
	s_cmp_lg_u32 s21, 0
	s_cbranch_scc0 .Lfl0
	v_cvt_pk_bf16_f32 v240, v236, v237
	global_store_dword v[238:239], v240, off

.Lpq1_end:
	s_and_b64 s[98:99], s[54:55], exec
	s_cbranch_scc0 .Lfl1
	v_cvt_pk_bf16_f32 v240, v236, v237
	global_store_dword v[238:239], v240, off
